# WP: phase-0 first w_in transpose item prefetches (1 dword per 128B line) the tile of the workgroup's second item (on v10)
# baseline (speedup 1.0000x reference)
; #define LAS __attribute__((address_space(3)))
; __device__ __forceinline__ int otid() { int t = threadIdx.x; asm volatile("" : "+v"(t)); return t; }
; #define GAS __attribute__((address_space(1)))
; __device__ __forceinline__ void transpose_tile(const float* W, int N, bf16_t* WT, int ldd, int kb, int nb, int upmap, LAS float* scr) {
;     const int tid = otid(), k0 = kb * 64, n0 = nb * 256;
;     GAS const float* src = (GAS const float*)(unsigned long long)W + (size_t)k0 * N + n0;
;     float tv[32];
; #pragma unroll
;     for (int i = 0; i < 32; ++i) { const int kk = i * 2 + (tid >> 8), nn = tid & 255; tv[i] = src[(size_t)kk * N + nn]; }
;     asm volatile("" ::: "memory");
; #pragma unroll
;     for (int i = 0; i < 32; ++i) { const int kk = i * 2 + (tid >> 8), nn = tid & 255; scr[kk * 257 + nn] = tv[i]; }
;     __syncthreads();
; __device__ void phase_prep(const Params& p, LAS unsigned char* lds) {
;     ...
;         if (it < I_TR) {
;             const int l = it / T_L; int j = it % T_L;
;             unsigned char* wb = p.ws + OFF_W + (size_t)l * LW;
;             if (j < T_IN) transpose_tile(p.w_in + (size_t)l * 1024 * INW, INW, (bf16_t*)(wb + LW_WIN), 1024, j / 17, j % 17, 0, scr);
.LBB0_732:
	s_andn2_b64 vcc, exec, s[4:5]
	s_cbranch_vccnz .LBB0_652
	s_cmp_lg_u32 s16, 0
	s_cbranch_scc1 .Lmy_wp_skip
	s_cmp_gt_u32 s6, 111
	s_cbranch_scc1 .Lmy_wp_skip
	s_add_i32 s1, s6, 160
	s_mul_i32 s4, s1, 0x7879
	s_lshr_b32 s4, s4, 19
	s_mul_i32 s5, s4, 17
	s_sub_i32 s1, s1, s5
	s_mul_i32 s4, s4, 0x110000
	s_lshl_b32 s1, s1, 10
	s_add_i32 s4, s4, s1
	v_lshrrev_b32_e32 v99, 3, v210
	v_and_b32_e32 v100, 7, v210
	v_mul_u32_u24_e32 v99, 0x4400, v99
	v_lshl_add_u32 v99, v100, 7, v99
	v_add_u32_e32 v100, s4, v99
	v_mov_b32_e32 v101, 0
	v_lshl_add_u64 v[100:101], v[18:19], 0, v[100:101]
	global_load_dword v102, v[100:101], off
.Lmy_wp_skip:
	s_mul_hi_i32 s11, s0, 0x1100000
	s_mul_i32 s10, s0, 0x1100000
	s_mul_i32 s0, s6, 0x7879
	s_lshr_b32 s1, s0, 31
	s_ashr_i32 s0, s0, 19
	s_add_i32 s0, s0, s1
	s_sext_i32_i16 s1, s0
	s_mul_i32 s0, s0, 17
	s_sub_i32 s0, s6, s0
	s_sext_i32_i16 s0, s0
	s_lshl_b32 s4, s1, 6
	s_lshl_b32 s0, s0, 8
	v_mov_b32_e32 v64, v210
	v_lshl_add_u64 v[2:3], s[10:11], 0, v[18:19]
	s_mul_i32 s6, s1, 0x110000
	s_mul_hi_i32 s7, s4, 0x4400
	s_ashr_i32 s1, s0, 31
	v_lshl_add_u64 v[2:3], v[2:3], 0, s[6:7]
	s_lshl_b64 s[6:7], s[0:1], 2
	v_lshlrev_b32_e32 v4, 2, v64
	v_lshl_add_u64 v[2:3], v[2:3], 0, s[6:7]
	v_ashrrev_i32_e32 v68, 8, v64
	v_and_b32_e32 v96, 0x3fc, v4
	v_lshl_add_u64 v[2:3], v[2:3], 0, v[96:97]
	v_mul_hi_i32_i24_e32 v5, 0x4400, v68
	v_mul_i32_i24_e32 v4, 0x4400, v68
	v_add_u32_e32 v52, 2, v68
	s_movk_i32 s1, 0x4400
	v_add_u32_e32 v54, 4, v68
	v_add_u32_e32 v56, 6, v68
	v_add_u32_e32 v58, 8, v68
	v_add_u32_e32 v60, 10, v68
	v_add_u32_e32 v62, 12, v68
	v_add_u32_e32 v66, 14, v68
	v_lshl_add_u64 v[4:5], v[2:3], 0, v[4:5]
	v_mad_i64_i32 v[52:53], s[6:7], v52, s1, v[2:3]
	v_mad_i64_i32 v[54:55], s[6:7], v54, s1, v[2:3]
	v_mad_i64_i32 v[56:57], s[6:7], v56, s1, v[2:3]
	v_mad_i64_i32 v[58:59], s[6:7], v58, s1, v[2:3]
	v_mad_i64_i32 v[60:61], s[6:7], v60, s1, v[2:3]
	v_mad_i64_i32 v[62:63], s[6:7], v62, s1, v[2:3]
	v_mad_i64_i32 v[66:67], s[6:7], v66, s1, v[2:3]
	global_load_dword v70, v[4:5], off
	global_load_dword v72, v[52:53], off
	global_load_dword v74, v[54:55], off
	global_load_dword v76, v[56:57], off
	global_load_dword v78, v[58:59], off
	global_load_dword v79, v[60:61], off
	global_load_dword v80, v[62:63], off
	global_load_dword v81, v[66:67], off
	v_add_u32_e32 v4, 16, v68
	v_add_u32_e32 v52, 18, v68
	v_add_u32_e32 v54, 20, v68
	v_add_u32_e32 v56, 22, v68
	v_add_u32_e32 v58, 24, v68
	v_add_u32_e32 v60, 26, v68
	v_add_u32_e32 v62, 28, v68
	v_add_u32_e32 v66, 30, v68
	v_mad_i64_i32 v[4:5], s[6:7], v4, s1, v[2:3]
	v_mad_i64_i32 v[52:53], s[6:7], v52, s1, v[2:3]
	v_mad_i64_i32 v[54:55], s[6:7], v54, s1, v[2:3]
	v_mad_i64_i32 v[56:57], s[6:7], v56, s1, v[2:3]
	v_mad_i64_i32 v[58:59], s[6:7], v58, s1, v[2:3]
	v_mad_i64_i32 v[60:61], s[6:7], v60, s1, v[2:3]
	v_mad_i64_i32 v[62:63], s[6:7], v62, s1, v[2:3]
	v_mad_i64_i32 v[66:67], s[6:7], v66, s1, v[2:3]
	global_load_dword v82, v[4:5], off
	global_load_dword v83, v[52:53], off
	global_load_dword v84, v[54:55], off
	global_load_dword v85, v[56:57], off
	global_load_dword v86, v[58:59], off
	global_load_dword v87, v[60:61], off
	global_load_dword v88, v[62:63], off
	global_load_dword v89, v[66:67], off
	v_add_u32_e32 v4, 32, v68
	v_add_u32_e32 v52, 34, v68
	v_add_u32_e32 v54, 36, v68
	v_add_u32_e32 v56, 38, v68
	v_add_u32_e32 v58, 40, v68
	v_add_u32_e32 v60, 42, v68
	v_add_u32_e32 v62, 44, v68
	v_add_u32_e32 v66, 46, v68
	v_mad_i64_i32 v[4:5], s[6:7], v4, s1, v[2:3]
	v_mad_i64_i32 v[52:53], s[6:7], v52, s1, v[2:3]
	v_mad_i64_i32 v[54:55], s[6:7], v54, s1, v[2:3]
	v_mad_i64_i32 v[56:57], s[6:7], v56, s1, v[2:3]
	v_mad_i64_i32 v[58:59], s[6:7], v58, s1, v[2:3]
	v_mad_i64_i32 v[60:61], s[6:7], v60, s1, v[2:3]
	v_mad_i64_i32 v[62:63], s[6:7], v62, s1, v[2:3]
	v_mad_i64_i32 v[66:67], s[6:7], v66, s1, v[2:3]
	global_load_dword v90, v[4:5], off
	global_load_dword v91, v[52:53], off
	global_load_dword v92, v[54:55], off
	global_load_dword v93, v[56:57], off
	global_load_dword v94, v[58:59], off
	global_load_dword v95, v[60:61], off
	global_load_dword v98, v[62:63], off
	s_nop 0
	global_load_dword v66, v[66:67], off
	v_add_u32_e32 v4, 48, v68
	v_add_u32_e32 v52, 50, v68
	v_add_u32_e32 v54, 52, v68
	v_add_u32_e32 v56, 54, v68
	v_add_u32_e32 v58, 56, v68
	v_add_u32_e32 v60, 58, v68
	v_add_u32_e32 v62, 60, v68
	v_add_u32_e32 v67, 62, v68
	v_mad_i64_i32 v[4:5], s[6:7], v4, s1, v[2:3]
	v_mad_i64_i32 v[52:53], s[6:7], v52, s1, v[2:3]
	v_mad_i64_i32 v[54:55], s[6:7], v54, s1, v[2:3]
	v_mad_i64_i32 v[56:57], s[6:7], v56, s1, v[2:3]
	v_mad_i64_i32 v[58:59], s[6:7], v58, s1, v[2:3]
	v_mad_i64_i32 v[60:61], s[6:7], v60, s1, v[2:3]
	v_mad_i64_i32 v[62:63], s[6:7], v62, s1, v[2:3]
	v_mad_i64_i32 v[2:3], s[6:7], v67, s1, v[2:3]
	global_load_dword v4, v[4:5], off
	s_nop 0
	global_load_dword v5, v[52:53], off
	s_nop 0
	global_load_dword v52, v[54:55], off
	global_load_dword v53, v[56:57], off
	s_nop 0
	global_load_dword v54, v[58:59], off
	global_load_dword v55, v[60:61], off
	global_load_dword v56, v[62:63], off
	s_nop 0
	global_load_dword v2, v[2:3], off
	v_mul_i32_i24_e32 v3, 0x404, v68
	v_add3_u32 v3, 0, v96, v3
	s_waitcnt vmcnt(0)
	ds_write_b32 v3, v70
	ds_write_b32 v3, v72 offset:2056
	ds_write_b32 v3, v74 offset:4112
	ds_write_b32 v3, v76 offset:6168
	ds_write_b32 v3, v78 offset:8224
	ds_write_b32 v3, v79 offset:10280
	ds_write_b32 v3, v80 offset:12336
	ds_write_b32 v3, v81 offset:14392
	ds_write_b32 v3, v82 offset:16448
	ds_write_b32 v3, v83 offset:18504
	ds_write_b32 v3, v84 offset:20560
	ds_write_b32 v3, v85 offset:22616
	ds_write_b32 v3, v86 offset:24672
	ds_write_b32 v3, v87 offset:26728
	ds_write_b32 v3, v88 offset:28784
	ds_write_b32 v3, v89 offset:30840
	ds_write_b32 v3, v90 offset:32896
	ds_write_b32 v3, v91 offset:34952
	ds_write_b32 v3, v92 offset:37008
	ds_write_b32 v3, v93 offset:39064
	ds_write_b32 v3, v94 offset:41120
	ds_write_b32 v3, v95 offset:43176
	ds_write_b32 v3, v98 offset:45232
	ds_write_b32 v3, v66 offset:47288
	ds_write_b32 v3, v4 offset:49344
	ds_write_b32 v3, v5 offset:51400
	ds_write_b32 v3, v52 offset:53456
	ds_write_b32 v3, v53 offset:55512
	ds_write_b32 v3, v54 offset:57568
	ds_write_b32 v3, v55 offset:59624
	ds_write_b32 v3, v56 offset:61680
	ds_write_b32 v3, v2 offset:63736
	v_lshlrev_b32_e32 v2, 3, v64
	v_ashrrev_i32_e32 v52, 3, v64
	v_and_b32_e32 v5, 56, v2
	v_mul_u32_u24_e32 v2, 0x404, v5
	v_lshlrev_b32_e32 v3, 2, v52
	v_add3_u32 v56, 0, v2, v3
	s_waitcnt lgkmcnt(0)
	s_barrier
; #define LAS __attribute__((address_space(3)))
; __device__ __forceinline__ unsigned pk2(float lo, float hi) { unsigned r; asm volatile("v_cvt_pk_bf16_f32 %0, %1, %2" : "=v"(r) : "v"(lo), "v"(hi)); return r; }
; #define GAS __attribute__((address_space(1)))
; __device__ __forceinline__ void transpose_tile(const float* W, int N, bf16_t* WT, int ldd, int kb, int nb, int upmap, LAS float* scr) {
;     ...
;     const int c = tid & 7;
;     GAS bf16_t* dst = (GAS bf16_t*)(unsigned long long)WT;
; #pragma unroll
;     for (int q = 0; q < 4; ++q) {
;         const int n = (tid >> 3) + 64 * q; const LAS float* sp = scr + (8 * c) * 257 + n;
;         u32x4 o; o.x = pk2(sp[0], sp[257]); o.y = pk2(sp[514], sp[771]); o.z = pk2(sp[1028], sp[1285]); o.w = pk2(sp[1542], sp[1799]);
;         int nd = n0 + n;
;         if (upmap) { nd = (nd < DFF) ? (256 * (nd >> 7) + (nd & 127)) : (256 * ((nd - DFF) >> 7) + 128 + ((nd - DFF) & 127)); }
;         *(GAS u32x4*)(dst + (size_t)nd * ldd + k0 + 8 * c) = o;
;     }
;     __syncthreads();
	ds_read_b32 v2, v56 offset:1028
	ds_read_b32 v3, v56
	s_waitcnt lgkmcnt(0)
	v_cvt_pk_bf16_f32 v2, v3, v2
	ds_read_b32 v3, v56 offset:3084
	ds_read_b32 v4, v56 offset:2056
	s_waitcnt lgkmcnt(0)
	v_cvt_pk_bf16_f32 v3, v4, v3
	ds_read_b32 v4, v56 offset:5140
	ds_read_b32 v53, v56 offset:4112
	s_waitcnt lgkmcnt(0)
	v_cvt_pk_bf16_f32 v4, v53, v4
	ds_read_b32 v53, v56 offset:7196
	ds_read_b32 v54, v56 offset:6168
	s_ashr_i32 s5, s4, 31
	v_lshlrev_b32_e32 v96, 1, v5
	s_waitcnt lgkmcnt(0)
	v_cvt_pk_bf16_f32 v5, v54, v53
	ds_read_b32 v57, v56 offset:1284
	ds_read_b32 v58, v56 offset:256
	s_lshl_b64 s[4:5], s[4:5], 1
	v_add_u32_e32 v52, s0, v52
	v_lshl_add_u64 v[50:51], v[50:51], 0, s[4:5]
	v_ashrrev_i32_e32 v53, 31, v52
	v_lshl_add_u64 v[50:51], v[50:51], 0, v[96:97]
	v_lshlrev_b64 v[54:55], 11, v[52:53]
	v_lshl_add_u64 v[54:55], v[50:51], 0, v[54:55]
	global_store_dwordx4 v[54:55], v[2:5], off
	v_add_u32_e32 v54, 64, v52
	v_ashrrev_i32_e32 v55, 31, v54
	s_waitcnt lgkmcnt(0)
	v_cvt_pk_bf16_f32 v2, v58, v57
	ds_read_b32 v3, v56 offset:3340
	ds_read_b32 v4, v56 offset:2312
	s_waitcnt lgkmcnt(0)
	v_cvt_pk_bf16_f32 v3, v4, v3
	ds_read_b32 v4, v56 offset:5396
	ds_read_b32 v5, v56 offset:4368
	s_waitcnt lgkmcnt(0)
	v_cvt_pk_bf16_f32 v4, v5, v4
	ds_read_b32 v5, v56 offset:7452
	ds_read_b32 v53, v56 offset:6424
	s_waitcnt lgkmcnt(0)
	v_cvt_pk_bf16_f32 v5, v53, v5
	ds_read_b32 v53, v56 offset:1540
	ds_read_b32 v57, v56 offset:512
	v_lshlrev_b64 v[54:55], 11, v[54:55]
	v_lshl_add_u64 v[54:55], v[50:51], 0, v[54:55]
	global_store_dwordx4 v[54:55], v[2:5], off
	v_add_u32_e32 v54, 0x80, v52
	v_ashrrev_i32_e32 v55, 31, v54
	s_waitcnt lgkmcnt(0)
	v_cvt_pk_bf16_f32 v2, v57, v53
	ds_read_b32 v3, v56 offset:3596
	ds_read_b32 v4, v56 offset:2568
	s_waitcnt lgkmcnt(0)
	v_cvt_pk_bf16_f32 v3, v4, v3
	ds_read_b32 v4, v56 offset:5652
	ds_read_b32 v5, v56 offset:4624
	s_waitcnt lgkmcnt(0)
	v_cvt_pk_bf16_f32 v4, v5, v4
	ds_read_b32 v5, v56 offset:7708
	ds_read_b32 v53, v56 offset:6680
	s_waitcnt lgkmcnt(0)
	v_cvt_pk_bf16_f32 v5, v53, v5
	ds_read_b32 v53, v56 offset:1796
	ds_read_b32 v57, v56 offset:768
	v_lshlrev_b64 v[54:55], 11, v[54:55]
	v_lshl_add_u64 v[54:55], v[50:51], 0, v[54:55]
	global_store_dwordx4 v[54:55], v[2:5], off
	v_add_u32_e32 v52, 0xc0, v52
	s_waitcnt lgkmcnt(0)
	v_cvt_pk_bf16_f32 v2, v57, v53
	ds_read_b32 v3, v56 offset:3852
	ds_read_b32 v4, v56 offset:2824
	s_waitcnt lgkmcnt(0)
	v_cvt_pk_bf16_f32 v3, v4, v3
	ds_read_b32 v4, v56 offset:5908
	ds_read_b32 v5, v56 offset:4880
	s_waitcnt lgkmcnt(0)
	v_cvt_pk_bf16_f32 v4, v5, v4
	ds_read_b32 v5, v56 offset:7964
	ds_read_b32 v53, v56 offset:6936
	s_waitcnt lgkmcnt(0)
	v_cvt_pk_bf16_f32 v5, v53, v5
	v_ashrrev_i32_e32 v53, 31, v52
	v_lshlrev_b64 v[52:53], 11, v[52:53]
	v_lshl_add_u64 v[50:51], v[50:51], 0, v[52:53]
	global_store_dwordx4 v[50:51], v[2:5], off
	s_barrier
	s_branch .LBB0_652
